# grid barrier: last XCD leader releases all XCC generation words itself; other leaders poll their own word (one hop less)
# baseline (speedup 1.0000x reference)
.LBB0_58:
	s_or_b64 exec, exec, s[12:13]
	v_cvt_f32_u32_e32 v5, v1
	s_waitcnt vmcnt(0)
	v_readfirstlane_b32 s6, v4
	v_sub_u32_e32 v4, 0, v1
	s_mov_b64 s[12:13], -1
	v_rcp_iflag_f32_e32 v5, v5
	v_add_u32_e32 v2, s6, v2
	v_add_u32_e32 v6, 1, v2
	v_mul_f32_e32 v5, 0x4f7ffffe, v5
	v_cvt_u32_f32_e32 v5, v5
	v_mul_lo_u32 v4, v4, v5
	v_mul_hi_u32 v4, v5, v4
	v_add_u32_e32 v4, v5, v4
	v_mul_hi_u32 v4, v2, v4
	v_mul_lo_u32 v5, v4, v1
	v_sub_u32_e32 v2, v2, v5
	v_add_u32_e32 v7, 1, v4
	v_sub_u32_e32 v5, v2, v1
	v_cmp_ge_u32_e32 vcc, v2, v1
	s_nop 1
	v_cndmask_b32_e32 v4, v4, v7, vcc
	v_cndmask_b32_e32 v2, v2, v5, vcc
	v_add_u32_e32 v5, 1, v4
	v_cmp_ge_u32_e32 vcc, v2, v1
	s_nop 1
	v_cndmask_b32_e32 v2, v4, v5, vcc
	v_mul_lo_u32 v4, v1, v2
	v_add_u32_e32 v1, v4, v1
	v_cmp_ne_u32_e32 vcc, v6, v1
	v_mov_b64_e32 v[4:5], s[76:77]
	v_readlane_b32 s100, v252, 62
	v_readlane_b32 s101, v252, 63
	s_and_saveexec_b64 s[6:7], vcc
	s_cbranch_execz .LBB0_70
	s_nop 4
	global_load_dword v1, v3, s[100:101] sc1
	s_mov_b64 s[14:15], 0
	s_waitcnt vmcnt(0)
	v_cmp_eq_u32_e32 vcc, v1, v2
	s_and_saveexec_b64 s[12:13], vcc
	s_cbranch_execz .LBB0_69
	s_mov_b32 s24, 1
	s_branch .LBB0_62

.LBB0_64:
	global_load_dword v1, v3, s[100:101] sc1
	s_add_i32 s24, s24, 1
	s_mov_b64 s[20:21], -1
	s_waitcnt vmcnt(0)
	v_cmp_ne_u32_e32 vcc, v1, v2
	s_orn2_b64 s[18:19], vcc, exec
	s_branch .LBB0_61

.LBB0_70:
	s_or_b64 exec, exec, s[6:7]
	s_and_saveexec_b64 s[6:7], s[12:13]
	s_cbranch_execz .LBB0_72
	global_atomic_add v[4:5], v205, off
	s_sub_u32 s100, s76, 0x1100
	s_subb_u32 s101, s77, 0
	global_atomic_add v3, v205, s[100:101]
	global_atomic_add v3, v205, s[100:101] offset:256
	global_atomic_add v3, v205, s[100:101] offset:512
	global_atomic_add v3, v205, s[100:101] offset:768
	global_atomic_add v3, v205, s[100:101] offset:1024
	global_atomic_add v3, v205, s[100:101] offset:1280
	global_atomic_add v3, v205, s[100:101] offset:1536
	global_atomic_add v3, v205, s[100:101] offset:1792
	global_atomic_add v3, v205, s[100:101] offset:2048
	global_atomic_add v3, v205, s[100:101] offset:2304
	global_atomic_add v3, v205, s[100:101] offset:2560
	global_atomic_add v3, v205, s[100:101] offset:2816
	global_atomic_add v3, v205, s[100:101] offset:3072
	global_atomic_add v3, v205, s[100:101] offset:3328
	global_atomic_add v3, v205, s[100:101] offset:3584
	global_atomic_add v3, v205, s[100:101] offset:3840
.LBB0_72:
	s_or_b64 exec, exec, s[6:7]
	s_mov_b64 s[6:7], exec
	v_mbcnt_lo_u32_b32 v1, s6, 0
	v_mbcnt_hi_u32_b32 v1, s7, v1
	v_cmp_eq_u32_e32 vcc, 0, v1
	s_and_saveexec_b64 s[12:13], vcc
	s_cbranch_execz .LBB0_74
	s_nop 0
